# attention units handed out from eight per-XCD queues (each XCD works on its own 32 batch-head groups so K/V stays in one L2, longest units first, empty queue falls over to the next XCD)
# speedup vs baseline: 1.0091x; 1.0091x over previous
.LBB0_794:
	s_or_b64 exec, exec, s[10:11]
	v_lshlrev_b32_e32 v2, 1, v66
	v_lshlrev_b32_e32 v4, 2, v66
	v_and_b32_e32 v5, 4, v64
	s_lshl_b32 s12, s35, 14
	v_and_b32_e32 v3, 48, v2
	v_and_b32_e32 v4, 8, v4
	v_and_or_b32 v2, v2, 2, v5
	s_add_i32 s12, s12, 0
	v_or3_b32 v2, v2, v4, v3
	v_and_b32_e32 v180, 31, v64
	v_mov_b32_e32 v3, s12
	v_lshl_add_u32 v181, v2, 1, s12
	s_movk_i32 s12, 0x90
	v_lshrrev_b32_e32 v1, 5, v66
	v_mad_u32_u24 v203, v180, s12, v3
	v_not_b32_e32 v3, 16
	v_mad_i32_i24 v217, v1, -4, v3
	v_not_b32_e32 v3, 17
	v_mad_i32_i24 v218, v1, -4, v3
	v_not_b32_e32 v3, 18
	v_mad_i32_i24 v219, v1, -4, v3
	v_not_b32_e32 v3, 23
	v_lshlrev_b32_e32 v0, 3, v1
	v_mad_i32_i24 v220, v1, -4, v3
	v_not_b32_e32 v3, 24
	v_or_b32_e32 v2, 16, v0
	v_mad_i32_i24 v221, v1, -4, v3
	v_not_b32_e32 v3, 25
	v_lshlrev_b32_e32 v182, 1, v0
	v_mbcnt_lo_u32_b32 v0, -1, 0
	v_mad_i32_i24 v222, v1, -4, v3
	v_not_b32_e32 v3, 26
	v_mbcnt_hi_u32_b32 v207, -1, v0
	v_mov_b32_e32 v183, 0
	v_mul_i32_i24_e32 v202, -4, v1
	v_lshlrev_b32_e32 v204, 4, v1
	v_mad_i32_i24 v205, v1, -4, -1
	v_mad_i32_i24 v210, v1, -4, -2
	v_mad_i32_i24 v211, v1, -4, -3
	v_mad_i32_i24 v212, v1, -4, -8
	v_mad_i32_i24 v213, v1, -4, -9
	v_mad_i32_i24 v214, v1, -4, -10
	v_mad_i32_i24 v215, v1, -4, -11
	v_mad_i32_i24 v216, v1, -4, -16
	v_mad_i32_i24 v223, v1, -4, v3
	v_mul_u32_u24_e32 v224, 0x480, v1
	v_mul_u32_u24_e32 v225, 0x90, v2
	v_lshlrev_b32_e32 v2, 2, v1
	v_mad_i32_i24 v226, v1, -4, v180
	v_lshrrev_b32_e32 v1, 1, v64
	s_movk_i32 s17, 0x2c00
	v_mov_b64_e32 v[4:5], s[38:39]
	v_and_b32_e32 v0, 64, v207
	s_mov_b32 s15, 0
	v_cmp_eq_u32_e64 s[10:11], 0, v66
	v_lshlrev_b32_e32 v184, 1, v180
	v_mov_b32_e32 v185, v183
	v_and_b32_e32 v186, 16, v1
	v_mov_b32_e32 v187, v183
	v_mad_u64_u32 v[188:189], s[12:13], v180, s17, v[4:5]
	s_mov_b32 s26, 0x58000
	s_mov_b32 s27, 0x11f00000
	s_movk_i32 s28, 0xff80
	s_movk_i32 s29, 0xffa0
	s_mov_b32 s16, 0x3e38aa3b
	s_mov_b32 s30, 0xc2fc0000
	s_mov_b32 s31, 0xffff0000
	s_mov_b64 s[18:19], 0xb0000
	s_movk_i32 s35, 0x3000
	v_lshlrev_b32_e32 v190, 1, v2
	v_mov_b32_e32 v227, 0x2c00
	v_xor_b32_e32 v208, 32, v207
	v_add_u32_e32 v209, 64, v0
	v_mov_b32_e32 v228, 0x80
	v_mov_b32_e32 v229, 0xa0
	v_mov_b32_e32 v230, 0x42800000
	v_not_b32_e32 v231, 63
	s_waitcnt lgkmcnt(0)
	s_barrier
	s_getreg_b32 s100, hwreg(HW_REG_XCC_ID, 0, 3)
	s_mov_b32 s101, 0
	s_branch .LBB0_797

.LBB0_797:
.Lq_again:
	s_lshl_b32 s12, s100, 7
	s_add_i32 s12, s12, 0x8000
	v_mov_b32_e32 v0, s12
	v_mov_b32_e32 v1, 1
	s_and_saveexec_b64 s[12:13], s[10:11]
	global_atomic_add v1, v0, v1, s[38:39] sc0
	s_or_b64 exec, exec, s[12:13]
	s_waitcnt vmcnt(0)
	v_readfirstlane_b32 s43, v1
	s_cmpk_lt_u32 s43, 0x800
	s_cbranch_scc1 .Lq_got
	s_add_i32 s101, s101, 1
	s_add_i32 s100, s100, 1
	s_and_b32 s100, s100, 7
	s_cmp_lt_u32 s101, 8
	s_cbranch_scc1 .Lq_again
	s_mov_b64 s[12:13], -1
	s_branch .LBB0_796
.Lq_got:
	s_cmpk_lt_u32 s43, 0x700
	s_cbranch_scc0 .Lq_tail
	s_mul_hi_u32 s12, s43, 0x4924925
	s_mul_i32 s13, s12, 56
	s_sub_i32 s13, s43, s13
	s_add_i32 s13, s13, 8
	s_branch .Lq_mapped
.Lq_tail:
	s_sub_i32 s13, s43, 0x700
	s_bfe_u32 s12, s13, 0x50001
	s_lshr_b32 s14, s13, 6
	s_sub_i32 s14, 3, s14
	s_and_b32 s13, s13, 1
	s_lshl_b32 s14, s14, 1
	s_or_b32 s13, s13, s14
.Lq_mapped:
	s_lshl_b32 s12, s12, 3
	s_or_b32 s12, s12, s100
	s_lshl_b32 s12, s12, 6
	s_or_b32 s43, s12, s13
	s_ashr_i32 s12, s43, 9
	s_bfe_u32 s52, s43, 0x50001
	s_ashr_i32 s13, s12, 31
	s_lshl_b32 s14, s43, 5
	s_lshl_b64 s[20:21], s[12:13], 11
	s_lshl_b32 s13, s52, 6
	s_and_b32 s25, s14, 32
	s_or_b32 s13, s13, s25
	v_or_b32_e32 v0, s13, v180
	v_or_b32_e32 v2, s20, v0
	v_mov_b64_e32 v[0:1], s[50:51]
	v_mad_u64_u32 v[2:3], s[40:41], v2, s17, v[0:1]
	v_sub_u32_e64 v4, 8, s52 clamp
	s_bfe_u32 s42, s43, 0x30006
	s_add_i32 s41, s52, -8
	v_readfirstlane_b32 s13, v4
	s_mul_i32 s24, s42, 0x404
	s_add_i32 s54, s41, s13
	v_mad_i32_i24 v3, s21, v227, v3
	s_lshl_b32 s14, s42, 7
	s_add_i32 s24, s24, 0
	s_ashr_i32 s55, s54, 31
	v_lshl_add_u64 v[192:193], v[2:3], 0, s[14:15]
	s_add_i32 s24, s24, 0x20000
	s_lshl_b64 s[54:55], s[54:55], 6
	v_lshl_add_u64 v[2:3], v[192:193], 0, v[182:183]
	s_add_u32 s13, s54, s20
	global_load_dwordx4 v[108:111], v[2:3], off
	global_load_dwordx4 v[104:107], v[2:3], off offset:32
	global_load_dwordx4 v[100:103], v[2:3], off offset:64
	global_load_dwordx4 v[96:99], v[2:3], off offset:96
	v_or_b32_e32 v2, s13, v180
	s_addc_u32 s40, s55, s21
	v_mad_u64_u32 v[0:1], s[54:55], v2, s17, v[0:1]
	v_mad_i32_i24 v1, s40, v227, v1
	v_lshl_add_u64 v[0:1], v[0:1], 0, s[14:15]
	v_lshl_add_u64 v[0:1], v[0:1], 0, v[182:183]
	v_add_co_u32_e32 v2, vcc, s26, v0
	v_readfirstlane_b32 s40, v4
	s_nop 0
	v_addc_co_u32_e32 v3, vcc, 0, v1, vcc
	global_load_dwordx4 v[52:55], v[0:1], off offset:1024
	global_load_dwordx4 v[48:51], v[0:1], off offset:1056
	global_load_dwordx4 v[56:59], v[2:3], off offset:1024
	global_load_dwordx4 v[44:47], v[2:3], off offset:1056
	global_load_dwordx4 v[40:43], v[0:1], off offset:1088
	global_load_dwordx4 v[32:35], v[0:1], off offset:1120
	global_load_dwordx4 v[36:39], v[2:3], off offset:1088
	global_load_dwordx4 v[176:179], v[2:3], off offset:1120
	v_mov_b32_e32 v0, s24
	ds_read_b32 v194, v0 offset:1024
	v_cmp_lt_i32_e32 vcc, v208, v209
	s_cmp_eq_u32 s52, 0
	s_nop 0
	v_cndmask_b32_e32 v0, v207, v208, vcc
	v_lshlrev_b32_e32 v191, 2, v0
	s_cbranch_scc1 .LBB0_813
	s_min_u32 s13, s52, 8
	s_sub_i32 s52, s52, s13
	s_ashr_i32 s53, s52, 31
	s_lshl_b32 s14, s13, 6
	s_lshl_b64 s[54:55], s[52:53], 6
	s_add_u32 s54, s54, s20
	s_addc_u32 s55, s55, s21
	s_lshl_b32 s13, s43, 1
	s_and_b32 s43, s13, 0x380
	v_lshl_add_u64 v[0:1], s[54:55], 0, v[184:185]
	s_add_u32 s54, s38, s43
	s_addc_u32 s55, s39, 0
	s_mul_hi_i32 s13, s12, 0x1600000
	s_mul_i32 s12, s12, 0x1600000
	s_mul_hi_i32 s53, s52, 0xb0000
	s_mul_i32 s52, s52, 0xb0000
	v_mov_b64_e32 v[2:3], s[54:55]
	s_add_u32 s12, s12, s52
	v_mad_u64_u32 v[198:199], s[54:55], v0, s17, v[2:3]
	s_addc_u32 s13, s13, s53
	s_or_b32 s12, s12, s43
	v_mov_b32_e32 v233, 0
	s_waitcnt vmcnt(0)
	v_mov_b64_e32 v[112:113], v[176:177]
	v_mov_b64_e32 v[118:119], v[34:35]
	v_mov_b64_e32 v[126:127], v[38:39]
	v_mov_b64_e32 v[122:123], v[42:43]
	v_mov_b64_e32 v[130:131], v[46:47]
	v_mov_b64_e32 v[134:135], v[50:51]
	v_mov_b64_e32 v[142:143], v[58:59]
	v_mov_b64_e32 v[138:139], v[54:55]
	s_waitcnt lgkmcnt(0)
	v_mov_b32_e32 v196, v194
	v_mov_b32_e32 v197, v194
	v_add_u32_e32 v232, s25, v226
	v_mad_i32_i24 v199, v1, s17, v199
	v_lshl_add_u64 v[200:201], v[188:189], 0, s[12:13]
	v_mov_b32_e32 v234, 0xf149f2ca
	s_mov_b32 s43, 0
	v_mov_b32_e32 v16, 0
	v_mov_b32_e32 v17, v233
	v_mov_b32_e32 v18, v233
	v_mov_b32_e32 v19, v233
	v_mov_b32_e32 v20, v233
	v_mov_b32_e32 v21, v233
	v_mov_b32_e32 v22, v233
	v_mov_b32_e32 v23, v233
	v_mov_b32_e32 v24, v233
	v_mov_b32_e32 v25, v233
	v_mov_b32_e32 v26, v233
	v_mov_b32_e32 v27, v233
	v_mov_b32_e32 v28, v233
	v_mov_b32_e32 v29, v233
	v_mov_b32_e32 v30, v233
	v_mov_b32_e32 v31, v233
	v_mov_b32_e32 v0, 0
	v_mov_b32_e32 v1, v233
	v_mov_b32_e32 v2, v233
	v_mov_b32_e32 v3, v233
	v_mov_b32_e32 v4, v233
	v_mov_b32_e32 v5, v233
	v_mov_b32_e32 v6, v233
	v_mov_b32_e32 v7, v233
	v_mov_b32_e32 v8, v233
	v_mov_b32_e32 v9, v233
	v_mov_b32_e32 v10, v233
	v_mov_b32_e32 v11, v233
	v_mov_b32_e32 v12, v233
	v_mov_b32_e32 v13, v233
	v_mov_b32_e32 v14, v233
	v_mov_b32_e32 v15, v233
	v_mov_b64_e32 v[114:115], v[178:179]
	v_mov_b64_e32 v[116:117], v[32:33]
	v_mov_b64_e32 v[124:125], v[36:37]
	v_mov_b64_e32 v[120:121], v[40:41]
	v_mov_b64_e32 v[128:129], v[44:45]
	v_mov_b64_e32 v[132:133], v[48:49]
	v_mov_b64_e32 v[140:141], v[56:57]
	v_mov_b64_e32 v[136:137], v[52:53]
